# weight transpose in the in-proj ctx phase (this layer's down weights): 16 loads per pass issued together, counted waits before the LDS writes (was 2 loads per round trip)
# speedup vs baseline: 1.0072x; 1.0072x over previous
; template <class RM> __device__ __forceinline__ void transpose_weight(const float* W, int K, int N, bf16_t* WT, RM rm, LAS float* scr, int gw, int ngw, int lane) {
;     ...
;     for (int it = gw; it < items; it += ngw) {
;         const int kb = it / nblk, nb = it % nblk, k0 = 64 * kb, n0 = 32 * nb;
; #pragma unroll 8
;         for (int i = 0; i < 32; ++i) { const int kk = 2 * i + (lane >> 5); scr[kk * 33 + (lane & 31)] = W[(size_t)(k0 + kk) * N + n0 + (lane & 31)]; }
;         asm volatile("s_waitcnt lgkmcnt(0)" ::: "memory");
.LBB0_234:
	s_lshl_b32 s9, s3, 1
	s_lshl_b32 s7, s2, 1
	s_add_i32 s3, s3, 16
	s_add_i32 s2, s2, 16
	s_add_i32 s4, s4, -16
	s_add_i32 s11, s9, 0
	s_add_i32 s10, s7, 0
	v_or_b32_e32 v18, s11, v10
	v_or_b32_e32 v16, s10, v5
	v_ashrrev_i32_e32 v19, 31, v18
	v_ashrrev_i32_e32 v17, 31, v16
	v_lshlrev_b64 v[18:19], 12, v[18:19]
	v_lshlrev_b64 v[16:17], 12, v[16:17]
	v_lshl_add_u64 v[18:19], v[8:9], 0, v[18:19]
	v_lshl_add_u64 v[16:17], v[8:9], 0, v[16:17]
	global_load_dword v40, v[18:19], off
	global_load_dword v41, v[16:17], off
	s_add_i32 s11, s9, 4
	s_add_i32 s10, s7, 4
	v_or_b32_e32 v18, s11, v10
	v_or_b32_e32 v16, s10, v5
	v_ashrrev_i32_e32 v19, 31, v18
	v_ashrrev_i32_e32 v17, 31, v16
	v_lshlrev_b64 v[18:19], 12, v[18:19]
	v_lshlrev_b64 v[16:17], 12, v[16:17]
	v_lshl_add_u64 v[18:19], v[8:9], 0, v[18:19]
	v_lshl_add_u64 v[16:17], v[8:9], 0, v[16:17]
	global_load_dword v42, v[18:19], off
	global_load_dword v43, v[16:17], off
	s_add_i32 s11, s9, 8
	s_add_i32 s10, s7, 8
	v_or_b32_e32 v18, s11, v10
	v_or_b32_e32 v16, s10, v5
	v_ashrrev_i32_e32 v19, 31, v18
	v_ashrrev_i32_e32 v17, 31, v16
	v_lshlrev_b64 v[18:19], 12, v[18:19]
	v_lshlrev_b64 v[16:17], 12, v[16:17]
	v_lshl_add_u64 v[18:19], v[8:9], 0, v[18:19]
	v_lshl_add_u64 v[16:17], v[8:9], 0, v[16:17]
	global_load_dword v44, v[18:19], off
	global_load_dword v45, v[16:17], off
	s_add_i32 s11, s9, 12
	s_add_i32 s10, s7, 12
	v_or_b32_e32 v18, s11, v10
	v_or_b32_e32 v16, s10, v5
	v_ashrrev_i32_e32 v19, 31, v18
	v_ashrrev_i32_e32 v17, 31, v16
	v_lshlrev_b64 v[18:19], 12, v[18:19]
	v_lshlrev_b64 v[16:17], 12, v[16:17]
	v_lshl_add_u64 v[18:19], v[8:9], 0, v[18:19]
	v_lshl_add_u64 v[16:17], v[8:9], 0, v[16:17]
	global_load_dword v46, v[18:19], off
	global_load_dword v47, v[16:17], off
	s_add_i32 s11, s9, 16
	s_add_i32 s10, s7, 16
	v_or_b32_e32 v18, s11, v10
	v_or_b32_e32 v16, s10, v5
	v_ashrrev_i32_e32 v19, 31, v18
	v_ashrrev_i32_e32 v17, 31, v16
	v_lshlrev_b64 v[18:19], 12, v[18:19]
	v_lshlrev_b64 v[16:17], 12, v[16:17]
	v_lshl_add_u64 v[18:19], v[8:9], 0, v[18:19]
	v_lshl_add_u64 v[16:17], v[8:9], 0, v[16:17]
	global_load_dword v48, v[18:19], off
	global_load_dword v49, v[16:17], off
	s_add_i32 s11, s9, 20
	s_add_i32 s10, s7, 20
	v_or_b32_e32 v18, s11, v10
	v_or_b32_e32 v16, s10, v5
	v_ashrrev_i32_e32 v19, 31, v18
	v_ashrrev_i32_e32 v17, 31, v16
	v_lshlrev_b64 v[18:19], 12, v[18:19]
	v_lshlrev_b64 v[16:17], 12, v[16:17]
	v_lshl_add_u64 v[18:19], v[8:9], 0, v[18:19]
	v_lshl_add_u64 v[16:17], v[8:9], 0, v[16:17]
	global_load_dword v50, v[18:19], off
	global_load_dword v51, v[16:17], off
	s_add_i32 s11, s9, 24
	s_add_i32 s10, s7, 24
	v_or_b32_e32 v18, s11, v10
	v_or_b32_e32 v16, s10, v5
	v_ashrrev_i32_e32 v19, 31, v18
	v_ashrrev_i32_e32 v17, 31, v16
	v_lshlrev_b64 v[18:19], 12, v[18:19]
	v_lshlrev_b64 v[16:17], 12, v[16:17]
	v_lshl_add_u64 v[18:19], v[8:9], 0, v[18:19]
	v_lshl_add_u64 v[16:17], v[8:9], 0, v[16:17]
	global_load_dword v52, v[18:19], off
	global_load_dword v53, v[16:17], off
	s_add_i32 s11, s9, 28
	s_add_i32 s10, s7, 28
	v_or_b32_e32 v18, s11, v10
	v_or_b32_e32 v16, s10, v5
	v_ashrrev_i32_e32 v19, 31, v18
	v_ashrrev_i32_e32 v17, 31, v16
	v_lshlrev_b64 v[18:19], 12, v[18:19]
	v_lshlrev_b64 v[16:17], 12, v[16:17]
	v_lshl_add_u64 v[18:19], v[8:9], 0, v[18:19]
	v_lshl_add_u64 v[16:17], v[8:9], 0, v[16:17]
	global_load_dword v54, v[18:19], off
	global_load_dword v55, v[16:17], off
	s_add_i32 s11, s9, 0
	s_add_i32 s10, s7, 0
	v_or_b32_e32 v21, s11, v0
	v_or_b32_e32 v20, s10, v1
	v_mad_u64_u32 v[16:17], s[10:11], v21, s97, v[4:5]
	v_mad_u64_u32 v[18:19], s[10:11], v20, s97, v[4:5]
	s_waitcnt vmcnt(14)
	ds_write_b32 v16, v40
	ds_write_b32 v18, v41
	s_add_i32 s11, s9, 4
	s_add_i32 s10, s7, 4
	v_or_b32_e32 v21, s11, v0
	v_or_b32_e32 v20, s10, v1
	v_mad_u64_u32 v[16:17], s[10:11], v21, s97, v[4:5]
	v_mad_u64_u32 v[18:19], s[10:11], v20, s97, v[4:5]
	s_waitcnt vmcnt(12)
	ds_write_b32 v16, v42
	ds_write_b32 v18, v43
	s_add_i32 s11, s9, 8
	s_add_i32 s10, s7, 8
	v_or_b32_e32 v21, s11, v0
	v_or_b32_e32 v20, s10, v1
	v_mad_u64_u32 v[16:17], s[10:11], v21, s97, v[4:5]
	v_mad_u64_u32 v[18:19], s[10:11], v20, s97, v[4:5]
	s_waitcnt vmcnt(10)
	ds_write_b32 v16, v44
	ds_write_b32 v18, v45
	s_add_i32 s11, s9, 12
	s_add_i32 s10, s7, 12
	v_or_b32_e32 v21, s11, v0
	v_or_b32_e32 v20, s10, v1
	v_mad_u64_u32 v[16:17], s[10:11], v21, s97, v[4:5]
	v_mad_u64_u32 v[18:19], s[10:11], v20, s97, v[4:5]
	s_waitcnt vmcnt(8)
	ds_write_b32 v16, v46
	ds_write_b32 v18, v47
	s_add_i32 s11, s9, 16
	s_add_i32 s10, s7, 16
	v_or_b32_e32 v21, s11, v0
	v_or_b32_e32 v20, s10, v1
	v_mad_u64_u32 v[16:17], s[10:11], v21, s97, v[4:5]
	v_mad_u64_u32 v[18:19], s[10:11], v20, s97, v[4:5]
	s_waitcnt vmcnt(6)
	ds_write_b32 v16, v48
	ds_write_b32 v18, v49
	s_add_i32 s11, s9, 20
	s_add_i32 s10, s7, 20
	v_or_b32_e32 v21, s11, v0
	v_or_b32_e32 v20, s10, v1
	v_mad_u64_u32 v[16:17], s[10:11], v21, s97, v[4:5]
	v_mad_u64_u32 v[18:19], s[10:11], v20, s97, v[4:5]
	s_waitcnt vmcnt(4)
	ds_write_b32 v16, v50
	ds_write_b32 v18, v51
	s_add_i32 s11, s9, 24
	s_add_i32 s10, s7, 24
	v_or_b32_e32 v21, s11, v0
	v_or_b32_e32 v20, s10, v1
	v_mad_u64_u32 v[16:17], s[10:11], v21, s97, v[4:5]
	v_mad_u64_u32 v[18:19], s[10:11], v20, s97, v[4:5]
	s_waitcnt vmcnt(2)
	ds_write_b32 v16, v52
	ds_write_b32 v18, v53
	s_add_i32 s11, s9, 28
	s_add_i32 s10, s7, 28
	v_or_b32_e32 v21, s11, v0
	v_or_b32_e32 v20, s10, v1
	v_mad_u64_u32 v[16:17], s[10:11], v21, s97, v[4:5]
	v_mad_u64_u32 v[18:19], s[10:11], v20, s97, v[4:5]
	s_waitcnt vmcnt(0)
	ds_write_b32 v16, v54
	ds_write_b32 v18, v55
	s_cmp_lg_u32 s4, 0
	s_cbranch_scc1 .LBB0_234
; __device__ __forceinline__ unsigned pk2(float lo, float hi) { f32x2_pk v = {lo, hi}; bf16x2_pk b = __builtin_convertvector(v, bf16x2_pk); return __builtin_bit_cast(unsigned, b); }
; #define LAS __attribute__((address_space(3)))
; template <class RM> __device__ __forceinline__ void transpose_weight(const float* W, int K, int N, bf16_t* WT, RM rm, LAS float* scr, int gw, int ngw, int lane) {
;     ...
;         asm volatile("s_waitcnt lgkmcnt(0)" ::: "memory");
;         const int c = lane & 7;
; #pragma unroll
;         for (int j = 0; j < 4; ++j) { const int n = (lane >> 3) + 8 * j; const LAS float* s = scr + (8 * c) * 33 + n;
;             u32x4 o; o.x = pk2(s[0 * 33], s[1 * 33]); o.y = pk2(s[2 * 33], s[3 * 33]); o.z = pk2(s[4 * 33], s[5 * 33]); o.w = pk2(s[6 * 33], s[7 * 33]);
;             *(u32x4*)(WT + (size_t)rm(n0 + n) * K + k0 + 8 * c) = o; }
;         asm volatile("s_waitcnt lgkmcnt(0)" ::: "memory");
;     }
	s_waitcnt lgkmcnt(0)
	ds_read2_b32 v[20:21], v12 offset0:33 offset1:41
	ds_read2_b32 v[22:23], v12 offset1:8
	ds_read2_b32 v[24:25], v12 offset0:66 offset1:74
	ds_read2_b32 v[26:27], v12 offset0:99 offset1:107
	ds_read2_b32 v[28:29], v12 offset0:132 offset1:140
	ds_read2_b32 v[30:31], v12 offset0:165 offset1:173
	ds_read2_b32 v[32:33], v12 offset0:198 offset1:206
	ds_read2_b32 v[34:35], v12 offset0:231 offset1:239
	v_or_b32_e32 v5, s6, v11
	s_ashr_i32 s9, s8, 31
	v_mul_lo_u32 v36, v5, s12
	v_lshl_add_u64 v[8:9], s[8:9], 1, v[6:7]
	v_ashrrev_i32_e32 v37, 31, v36
	v_or_b32_e32 v5, s6, v13
	s_waitcnt lgkmcnt(6)
	v_cvt_pk_bf16_f32 v16, v22, v20
	s_waitcnt lgkmcnt(4)
	v_cvt_pk_bf16_f32 v17, v24, v26
	s_waitcnt lgkmcnt(2)
	v_cvt_pk_bf16_f32 v18, v28, v30
	s_waitcnt lgkmcnt(0)
	v_cvt_pk_bf16_f32 v19, v32, v34
	v_lshl_add_u64 v[36:37], v[36:37], 1, v[8:9]
	v_mul_lo_u32 v20, v5, s12
	global_store_dwordx4 v[36:37], v[16:19], off
	v_or_b32_e32 v5, s6, v14
	v_mul_lo_u32 v36, v5, s12
	v_cvt_pk_bf16_f32 v16, v23, v21
	v_ashrrev_i32_e32 v21, 31, v20
	v_cvt_pk_bf16_f32 v17, v25, v27
	v_cvt_pk_bf16_f32 v18, v29, v31
	v_cvt_pk_bf16_f32 v19, v33, v35
	v_lshl_add_u64 v[20:21], v[20:21], 1, v[8:9]
	global_store_dwordx4 v[20:21], v[16:19], off
	ds_read2_b32 v[20:21], v12 offset0:49 offset1:57
	ds_read2_b32 v[22:23], v12 offset0:16 offset1:24
	ds_read2_b32 v[24:25], v12 offset0:82 offset1:90
	ds_read2_b32 v[26:27], v12 offset0:115 offset1:123
	ds_read2_b32 v[28:29], v12 offset0:148 offset1:156
	ds_read2_b32 v[30:31], v12 offset0:181 offset1:189
	ds_read2_b32 v[32:33], v12 offset0:214 offset1:222
	ds_read2_b32 v[34:35], v12 offset0:247 offset1:255
	v_ashrrev_i32_e32 v37, 31, v36
	v_or_b32_e32 v5, s6, v15
	s_waitcnt lgkmcnt(6)
	v_cvt_pk_bf16_f32 v16, v22, v20
	s_waitcnt lgkmcnt(4)
	v_cvt_pk_bf16_f32 v17, v24, v26
	s_waitcnt lgkmcnt(2)
	v_cvt_pk_bf16_f32 v18, v28, v30
	s_waitcnt lgkmcnt(0)
	v_cvt_pk_bf16_f32 v19, v32, v34
	v_lshl_add_u64 v[36:37], v[36:37], 1, v[8:9]
	v_mul_lo_u32 v20, v5, s12
	global_store_dwordx4 v[36:37], v[16:19], off
	s_sub_i32 s2, s1, s72
	s_add_i32 s1, s2, 0x800
	v_cvt_pk_bf16_f32 v16, v23, v21
	v_ashrrev_i32_e32 v21, 31, v20
	v_cvt_pk_bf16_f32 v17, v25, v27
	v_cvt_pk_bf16_f32 v18, v29, v31
	v_cvt_pk_bf16_f32 v19, v33, v35
	v_lshl_add_u64 v[8:9], v[20:21], 1, v[8:9]
	global_store_dwordx4 v[8:9], v[16:19], off
	s_waitcnt lgkmcnt(0)
	s_cmpk_lt_i32 s2, 0xfd80
	s_cbranch_scc1 .LBB0_233
